# phase-7 own conversion loops: the two 'up' matrices start from the opposite end of the wave range (SWA-half item balance)
# baseline (speedup 1.0000x reference)
; #define LAS __attribute__((address_space(3)))
; __device__ __forceinline__ void conv_matrix(const float* W, int K, int N, const float* gain, bf16_t* WT, int Kd, int mode, int row_off, LAS float* scr, int lane, int gw, int NGW) {
;     const int nblk = N / 32, items = nblk * (K / 64);
;     for (int it = gw; it < items; it += NGW) {
;         const int kb = it / nblk, nb = it % nblk, k0 = 64 * kb, n0 = 32 * nb;
;         float wv[32];
; #pragma unroll
;         for (int i = 0; i < 32; ++i) wv[i] = W[(size_t)(k0 + 2 * i + (lane >> 5)) * N + n0 + (lane & 31)];
.LBB0_718:
	v_lshlrev_b32_e32 v6, 2, v6
	v_mov_b32_e32 v7, v0
	v_lshl_add_u64 v[2:3], v[2:3], 0, v[6:7]
	s_mov_b64 s[0:1], 0x2c00000
	v_lshl_add_u64 v[2:3], v[2:3], 0, s[0:1]
	s_sub_i32 s19, s8, s2
	s_add_i32 s19, s19, -1
	s_lshl_b32 s18, s19, 5
	s_lshl_b32 s12, s19, 6
	s_branch .LBB0_720

; #define LAS __attribute__((address_space(3)))
; __device__ __forceinline__ void conv_matrix(const float* W, int K, int N, const float* gain, bf16_t* WT, int Kd, int mode, int row_off, LAS float* scr, int lane, int gw, int NGW) {
;     const int nblk = N / 32, items = nblk * (K / 64);
;     for (int it = gw; it < items; it += NGW) {
;         const int kb = it / nblk, nb = it % nblk, k0 = 64 * kb, n0 = 32 * nb;
;         float wv[32];
; #pragma unroll
;         for (int i = 0; i < 32; ++i) wv[i] = W[(size_t)(k0 + 2 * i + (lane >> 5)) * N + n0 + (lane & 31)];
.LBB0_728:
	v_mov_b32_e32 v7, v0
	v_lshl_add_u64 v[2:3], v[2:3], 0, v[6:7]
	s_mov_b64 s[0:1], 0x2c00000
	v_lshl_add_u64 v[2:3], v[2:3], 0, s[0:1]
	s_sub_i32 s19, s8, s2
	s_add_i32 s19, s19, -1
	s_lshl_b32 s18, s19, 5
	s_lshl_b32 s16, s19, 6
	s_branch .LBB0_730
